# adds G10 epilogue gate-load hoist (no per-row-group vmcnt(0) drain) and SGU chunk prologue: six LN-parameter loads issued together
# baseline (speedup 1.0000x reference)
; #define LAS __attribute__((address_space(3)))
; __device__ __forceinline__ void sgu_pool_chunk(KArgs A, int l, int chunk, LAS unsigned char* lds) {
;     ...
;     const float* lng = A->in[7] + (size_t)l * D_; const float* lnb = A->in[8] + (size_t)l * D_;
;     const float* sw = A->in[9] + (size_t)l * 8 * 128 * 128; const float* sb = A->in[10] + (size_t)l * 8 * 128;
;     const int t0 = chunk * 128;
;     LAS float* st_mean = (LAS float*)(lds + 2 * 128 * 272);
;     LAS float* st_rstd = st_mean + 128;
;     LAS float* gL = st_rstd + 128;
;     LAS float* bL = gL + D_; LAS float* sbL = bL + D_;
;     for (int i = tid; i < D_; i += 512) { gL[i] = lng[i]; bL[i] = lnb[i]; sbL[i] = sb[i]; }
.LBB0_323:
	v_ashrrev_i32_e32 v9, 31, v0
	v_mov_b32_e32 v8, v0
	v_ashrrev_i32_e32 v7, 31, v1
	v_mov_b32_e32 v6, v1
	v_lshlrev_b64 v[8:9], 2, v[8:9]
	v_lshlrev_b64 v[6:7], 2, v[6:7]
	v_lshl_add_u64 v[10:11], s[22:23], 0, v[8:9]
	v_lshl_add_u64 v[12:13], s[22:23], 0, v[6:7]
	global_load_dword v14, v[10:11], off
	global_load_dword v15, v[12:13], off
	v_lshl_add_u64 v[10:11], s[24:25], 0, v[8:9]
	v_lshl_add_u64 v[12:13], s[24:25], 0, v[6:7]
	global_load_dword v16, v[10:11], off
	global_load_dword v17, v[12:13], off
	v_lshl_add_u64 v[8:9], s[4:5], 0, v[8:9]
	v_lshl_add_u64 v[6:7], s[4:5], 0, v[6:7]
	global_load_dword v18, v[8:9], off
	global_load_dword v19, v[6:7], off
	v_add_u32_e32 v4, -2, v4
	v_cmp_eq_u32_e32 vcc, 0, v4
	v_add_u32_e32 v1, 0x400, v1
	v_add_u32_e32 v0, 0x400, v0
	s_or_b64 s[26:27], vcc, s[26:27]
	v_add_u32_e32 v12, 0x1000, v5
	s_waitcnt vmcnt(4)
	ds_write2st64_b32 v5, v14, v15 offset1:8
	s_waitcnt vmcnt(2)
	ds_write2st64_b32 v5, v16, v17 offset0:16 offset1:24
	s_waitcnt vmcnt(0)
	ds_write2st64_b32 v5, v18, v19 offset0:32 offset1:40
	v_mov_b32_e32 v5, v12
	s_andn2_b64 exec, exec, s[26:27]
	s_cbranch_execnz .LBB0_323
	s_or_b64 exec, exec, s[26:27]
	v_cmp_ne_u32_e32 vcc, v2, v3
	v_lshl_add_u32 v0, v3, 9, v64
	s_orn2_b64 s[22:23], vcc, exec
